# dprep l2norm sums via DPP+readlane; LN mode-1 w8s staging 16 loads in flight; gate loop waits for its prefetch at the end of the iteration
# speedup vs baseline: 1.0402x; 1.0103x over previous
; DI const float* INP(const Args& a, int i) { asm volatile("" : "+s"(i)); return a.in[i]; }
; DI unsigned pk2(float a, float b) { f32x2 v = {a, b}; nbf2 r = __builtin_convertvector(v, nbf2); return __builtin_bit_cast(unsigned, r); }
; DI float bflo(unsigned w) { return __uint_as_float(w << 16); }
; DI float bfhi(unsigned w) { return __uint_as_float(w & 0xffff0000u); }
; DI float silu_f(float x) { return x * __builtin_amdgcn_rcpf(1.f + __expf(-x)); }
; DI void gate_phase(const Args& a, int l) {
;     ...
;     const float* og = INP(a, 14) + l * 128 + (lane & 15) * 8;
;     const f32x4 g0 = *(const f32x4*)og, g1 = *(const f32x4*)(og + 4);
;     f32x4 n0 = {0.f, 0.f, 0.f, 0.f}, n1 = {0.f, 0.f, 0.f, 0.f}; u32x4 nz = {0u, 0u, 0u, 0u};
;     { const int row = blockIdx.x * 8 + wave; if (row < NVALID) { n0 = *(const f32x4*)(O + (size_t)row * 512 + lane * 8); n1 = *(const f32x4*)(O + (size_t)row * 512 + lane * 8 + 4); nz = *(const u32x4*)(PROJ + (size_t)row * NPROJ + 1536 + lane * 8); } }
;     for (int row = blockIdx.x * 8 + wave; row < NVALID; row += gridDim.x * 8) {
;         const f32x4 o0 = n0, o1 = n1; const u32x4 zr = nz;
;         { const int nrow = row + gridDim.x * 8; if (nrow < NVALID) { n0 = *(const f32x4*)(O + (size_t)nrow * 512 + lane * 8); n1 = *(const f32x4*)(O + (size_t)nrow * 512 + lane * 8 + 4); nz = *(const u32x4*)(PROJ + (size_t)nrow * NPROJ + 1536 + lane * 8); } }
;         float ss = (o0[0] * o0[0] + o0[1] * o0[1]) + (o0[2] * o0[2] + o0[3] * o0[3]) + (o1[0] * o1[0] + o1[1] * o1[1]) + (o1[2] * o1[2] + o1[3] * o1[3]);
;         ss += __shfl_xor(ss, 8); ss += __shfl_xor(ss, 4); ss += __shfl_xor(ss, 2); ss += __shfl_xor(ss, 1);
;         const float rs = rsqrtf(ss * (1.f / 128.f) + 1e-6f);
;         float r[8];
;         r[0] = o0[0] * rs * g0[0] * silu_f(bflo(zr.x)); r[1] = o0[1] * rs * g0[1] * silu_f(bfhi(zr.x));
;         r[2] = o0[2] * rs * g0[2] * silu_f(bflo(zr.y)); r[3] = o0[3] * rs * g0[3] * silu_f(bfhi(zr.y));
;         r[4] = o1[0] * rs * g1[0] * silu_f(bflo(zr.z)); r[5] = o1[1] * rs * g1[1] * silu_f(bfhi(zr.z));
;         r[6] = o1[2] * rs * g1[2] * silu_f(bflo(zr.w)); r[7] = o1[3] * rs * g1[3] * silu_f(bfhi(zr.w));
;         u32x4 wv; wv.x = pk2(r[0], r[1]); wv.y = pk2(r[2], r[3]); wv.z = pk2(r[4], r[5]); wv.w = pk2(r[6], r[7]);
;         *(u32x4*)(MIX + (size_t)row * DM + lane * 8) = wv;
.LBB0_92:
	s_andn2_b64 vcc, exec, s[8:9]
	s_cbranch_vccnz .LBB0_99
	s_waitcnt vmcnt(0)
	v_mov_b32_e32 v0, v152
	v_readlane_b32 s9, v254, 54
	v_ashrrev_i32_e32 v1, 6, v0
	s_mov_b32 s8, 14
	v_add_u32_e32 v32, s9, v1
	s_movk_i32 s9, 0x4080
	v_cmp_gt_i32_e32 vcc, s9, v32
	s_and_saveexec_b64 s[10:11], vcc
	s_cbranch_execz .LBB0_98
	s_ashr_i32 s9, s8, 31
	s_lshl_b64 s[8:9], s[8:9], 3
	s_add_u32 s8, s0, s8
	s_addc_u32 s9, s1, s9
	s_load_dwordx2 s[8:9], s[8:9], 0x0
	s_lshl_b32 s12, s25, 7
	s_ashr_i32 s13, s12, 31
	v_lshlrev_b32_e32 v2, 3, v0
	s_lshl_b64 s[12:13], s[12:13], 2
	v_lshlrev_b32_e32 v0, 5, v0
	v_ashrrev_i32_e32 v33, 31, v32
	v_readlane_b32 s14, v253, 50
	s_waitcnt lgkmcnt(0)
	s_add_u32 s8, s8, s12
	v_and_b32_e32 v4, 0x1e0, v0
	v_lshlrev_b64 v[0:1], 11, v[32:33]
	v_readlane_b32 s15, v253, 51
	v_and_b32_e32 v5, 0x1f8, v2
	v_mov_b64_e32 v[2:3], s[72:73]
	s_addc_u32 s9, s9, s13
	v_lshl_add_u64 v[0:1], s[14:15], 0, v[0:1]
	v_lshlrev_b32_e32 v128, 2, v5
	v_mad_i64_i32 v[2:3], s[12:13], v32, s42, v[2:3]
	v_lshlrev_b32_e32 v8, 1, v5
	v_mov_b32_e32 v9, v129
	v_lshl_add_u64 v[0:1], v[0:1], 0, v[128:129]
	v_lshl_add_u64 v[2:3], v[2:3], 0, v[8:9]
	global_load_dwordx4 v[24:27], v[2:3], off offset:3072
	global_load_dwordx4 v[20:23], v[0:1], off offset:16
	global_load_dwordx4 v[28:31], v[0:1], off
	s_nop 0
	global_load_dwordx4 v[0:3], v4, s[8:9]
	s_nop 0
	global_load_dwordx4 v[4:7], v4, s[8:9] offset:16
	v_and_b32_e32 v11, 64, v160
	v_xor_b32_e32 v10, 8, v160
	v_add_u32_e32 v11, 64, v11
	v_cmp_lt_i32_e32 vcc, v10, v11
	v_readlane_b32 s8, v253, 48
	v_readlane_b32 s9, v253, 49
	v_cndmask_b32_e32 v10, v160, v10, vcc
	v_lshlrev_b32_e32 v43, 2, v10
	v_xor_b32_e32 v10, 4, v160
	v_cmp_lt_i32_e32 vcc, v10, v11
	v_lshl_add_u64 v[36:37], s[8:9], 0, v[8:9]
	v_lshl_add_u64 v[38:39], s[72:73], 0, v[8:9]
	v_cndmask_b32_e32 v10, v160, v10, vcc
	v_lshlrev_b32_e32 v44, 2, v10
	v_xor_b32_e32 v10, 2, v160
	v_cmp_lt_i32_e32 vcc, v10, v11
	v_lshl_add_u64 v[34:35], s[14:15], 0, v[128:129]
	s_mov_b64 s[12:13], 0
	v_cndmask_b32_e32 v10, v160, v10, vcc
	v_lshlrev_b32_e32 v45, 2, v10
	v_xor_b32_e32 v10, 1, v160
	v_cmp_lt_i32_e32 vcc, v10, v11
	s_waitcnt vmcnt(4)
	v_mov_b64_e32 v[16:17], v[24:25]
	v_cndmask_b32_e32 v10, v160, v10, vcc
	v_lshlrev_b32_e32 v46, 2, v10
	s_waitcnt vmcnt(3)
	v_mov_b64_e32 v[8:9], v[20:21]
	s_waitcnt vmcnt(2)
	v_mov_b64_e32 v[12:13], v[28:29]
	v_mov_b64_e32 v[18:19], v[26:27]
	v_mov_b64_e32 v[10:11], v[22:23]
	v_mov_b64_e32 v[14:15], v[30:31]
	s_waitcnt vmcnt(0)
	s_branch .LBB0_96
.LBB0_95:
	s_or_b64 exec, exec, s[14:15]
	v_pk_mul_f32 v[48:49], v[30:31], v[30:31]
	v_pk_mul_f32 v[50:51], v[28:29], v[28:29]
	s_and_b64 s[8:9], exec, vcc
	v_pk_mov_b32 v[52:53], v[50:51], v[48:49] op_sel:[1,0]
	v_mov_b32_e32 v51, v49
	v_pk_add_f32 v[48:49], v[52:53], v[50:51]
	v_pk_mul_f32 v[50:51], v[22:23], v[22:23]
	v_pk_mul_f32 v[52:53], v[20:21], v[20:21]
	v_mov_b32_e32 v54, v50
	v_mov_b32_e32 v55, v52
	v_mov_b32_e32 v52, v51
	v_pk_add_f32 v[50:51], v[54:55], v[52:53]
	v_add_f32_e32 v33, v48, v49
	v_add_f32_e32 v33, v51, v33
	v_add_f32_e32 v33, v50, v33
	ds_bpermute_b32 v41, v43, v33
	v_lshlrev_b32_e32 v48, 16, v24
	v_and_b32_e32 v49, 0xffff0000, v24
	v_mul_f32_e32 v24, 0xbfb8aa3b, v48
	v_exp_f32_e32 v24, v24
	s_waitcnt lgkmcnt(0)
	v_add_f32_e32 v33, v33, v41
	ds_bpermute_b32 v41, v44, v33
	s_or_b64 s[12:13], s[8:9], s[12:13]
	v_add_f32_e32 v24, 1.0, v24
	v_rcp_f32_e32 v50, v24
	v_mul_f32_e32 v24, 0xbfb8aa3b, v49
	s_waitcnt lgkmcnt(0)
	v_add_f32_e32 v33, v33, v41
	ds_bpermute_b32 v41, v45, v33
	v_exp_f32_e32 v24, v24
	s_waitcnt lgkmcnt(0)
	v_add_f32_e32 v33, v33, v41
	ds_bpermute_b32 v41, v46, v33
	v_add_f32_e32 v24, 1.0, v24
	v_rcp_f32_e32 v51, v24
	v_lshlrev_b32_e32 v24, 16, v25
	v_and_b32_e32 v25, 0xffff0000, v25
	s_waitcnt lgkmcnt(0)
	v_add_f32_e32 v33, v33, v41
	v_fmamk_f32 v33, v33, 0x3c000000, v157
	v_cmp_gt_f32_e32 vcc, s46, v33
	v_mul_f32_e32 v41, 0x4b800000, v33
	v_pk_mul_f32 v[48:49], v[50:51], v[48:49]
	v_cndmask_b32_e32 v33, v33, v41, vcc
	v_rsq_f32_e32 v33, v33
	s_nop 0
	v_mul_f32_e32 v41, 0x45800000, v33
	v_cndmask_b32_e32 v42, v33, v41, vcc
	v_mul_f32_e32 v33, 0xbfb8aa3b, v24
	v_exp_f32_e32 v33, v33
	v_pk_mul_f32 v[28:29], v[28:29], v[42:43] op_sel_hi:[1,0]
	v_pk_mul_f32 v[30:31], v[30:31], v[42:43] op_sel_hi:[1,0]
	v_pk_mul_f32 v[28:29], v[0:1], v[28:29]
	v_add_f32_e32 v33, 1.0, v33
	v_pk_mul_f32 v[28:29], v[48:49], v[28:29]
	v_rcp_f32_e32 v48, v33
	v_mul_f32_e32 v33, 0xbfb8aa3b, v25
	v_exp_f32_e32 v33, v33
	v_pk_mul_f32 v[30:31], v[2:3], v[30:31]
	v_pk_mul_f32 v[20:21], v[20:21], v[42:43] op_sel_hi:[1,0]
	v_pk_mul_f32 v[22:23], v[22:23], v[42:43] op_sel_hi:[1,0]
	v_add_f32_e32 v33, 1.0, v33
	v_rcp_f32_e32 v49, v33
	v_pk_mul_f32 v[20:21], v[4:5], v[20:21]
	v_pk_mul_f32 v[22:23], v[6:7], v[22:23]
	v_ashrrev_i32_e32 v33, 31, v32
	v_pk_mul_f32 v[24:25], v[48:49], v[24:25]
	s_nop 0
	v_pk_mul_f32 v[24:25], v[24:25], v[30:31]
	v_lshlrev_b32_e32 v30, 16, v26
	v_and_b32_e32 v31, 0xffff0000, v26
	v_mul_f32_e32 v26, 0xbfb8aa3b, v30
	v_exp_f32_e32 v26, v26
	s_nop 0
	v_add_f32_e32 v26, 1.0, v26
	v_rcp_f32_e32 v48, v26
	v_mul_f32_e32 v26, 0xbfb8aa3b, v31
	v_exp_f32_e32 v26, v26
	s_nop 0
	v_add_f32_e32 v26, 1.0, v26
	v_rcp_f32_e32 v49, v26
	s_nop 0
	v_pk_mul_f32 v[30:31], v[48:49], v[30:31]
	s_nop 0
	v_pk_mul_f32 v[30:31], v[30:31], v[20:21]
	v_lshlrev_b32_e32 v20, 16, v27
	v_and_b32_e32 v21, 0xffff0000, v27
	v_mul_f32_e32 v26, 0xbfb8aa3b, v20
	v_mul_f32_e32 v27, 0xbfb8aa3b, v21
	v_exp_f32_e32 v26, v26
	v_exp_f32_e32 v27, v27
	v_add_f32_e32 v26, 1.0, v26
	v_add_f32_e32 v27, 1.0, v27
	v_rcp_f32_e32 v26, v26
	v_rcp_f32_e32 v27, v27
	s_nop 0
	v_pk_mul_f32 v[20:21], v[26:27], v[20:21]
	s_nop 0
	v_pk_mul_f32 v[26:27], v[20:21], v[22:23]
	v_cvt_pk_bf16_f32 v21, v24, v25
	v_lshlrev_b64 v[24:25], 11, v[32:33]
	v_cvt_pk_bf16_f32 v20, v28, v29
	v_cvt_pk_bf16_f32 v22, v30, v31
	v_cvt_pk_bf16_f32 v23, v26, v27
	v_lshl_add_u64 v[24:25], v[36:37], 0, v[24:25]
	global_store_dwordx4 v[24:25], v[20:23], off
	s_waitcnt vmcnt(1)
	v_mov_b64_e32 v[30:31], v[14:15]
	v_mov_b64_e32 v[26:27], v[18:19]
	v_mov_b64_e32 v[22:23], v[10:11]
	v_mov_b64_e32 v[28:29], v[12:13]
	v_mov_b64_e32 v[20:21], v[8:9]
	v_mov_b64_e32 v[24:25], v[16:17]
	v_mov_b32_e32 v32, v40
	s_andn2_b64 exec, exec, s[12:13]
	s_cbranch_execz .LBB0_98

; #define LAS __attribute__((address_space(3)))
; DI unsigned pk2(float a, float b) { f32x2 v = {a, b}; nbf2 r = __builtin_convertvector(v, nbf2); return __builtin_bit_cast(unsigned, r); }
; DI float bflo(unsigned w) { return __uint_as_float(w << 16); }
; DI float bfhi(unsigned w) { return __uint_as_float(w & 0xffff0000u); }
; DI float silu_f(float x) { return x * __builtin_amdgcn_rcpf(1.f + __expf(-x)); }
; DI void dprep_item(LAS unsigned char* ldsh, const Args& a, int l, int item, int tl) {
;     ...
;           for (int i = 0; i < 11; ++i) { const int tpos = n * 64 + rg * 8 - 3 + i;
;               if (tpos >= 0) { const u32x2 raw = *(const u32x2*)(PROJ + (size_t)(r0 + rg * 8 - 3 + i) * NPROJ + col); xin[i] = (f32x4){bflo(raw.x), bfhi(raw.x), bflo(raw.y), bfhi(raw.y)}; }
;               else xin[i] = (f32x4){0.f, 0.f, 0.f, 0.f}; }
;           LAS bf16_t* dst = sec == 0 ? qn : (sec == 1 ? kn : vv);
; #pragma unroll
;           for (int j = 0; j < 8; ++j) { f32x4 o = w[0] * xin[j] + w[1] * xin[j + 1] + w[2] * xin[j + 2] + w[3] * xin[j + 3];
;               o[0] = silu_f(o[0]); o[1] = silu_f(o[1]); o[2] = silu_f(o[2]); o[3] = silu_f(o[3]);
;               if (sec < 2) { float ss = (o[0] * o[0] + o[1] * o[1]) + (o[2] * o[2] + o[3] * o[3]);
;                   ss += __shfl_xor(ss, 16); ss += __shfl_xor(ss, 8); ss += __shfl_xor(ss, 4); ss += __shfl_xor(ss, 2); ss += __shfl_xor(ss, 1);
;                   const float sc = rsqrtf(ss + 1e-6f) * (sec == 0 ? 0.08838834764831845f : 1.f); o = o * sc; }
;               u32x2 pw; pw.x = pk2(o[0], o[1]); pw.y = pk2(o[2], o[3]); *(LAS u32x2*)(dst + (rg * 8 + j) * 136 + c0) = pw; }
.LBB0_237:
	s_or_b64 exec, exec, s[10:11]
	s_waitcnt vmcnt(0)
	v_lshlrev_b32_e32 v54, 16, v180
	v_and_b32_e32 v55, 0xffff0000, v180
	v_lshlrev_b32_e32 v62, 16, v181
	v_and_b32_e32 v63, 0xffff0000, v181
	v_lshlrev_b32_e32 v50, 16, v182
	v_and_b32_e32 v51, 0xffff0000, v182
	v_lshlrev_b32_e32 v66, 16, v183
	v_and_b32_e32 v67, 0xffff0000, v183
	v_lshlrev_b32_e32 v56, 16, v184
	v_and_b32_e32 v57, 0xffff0000, v184
	v_lshlrev_b32_e32 v60, 16, v185
	v_and_b32_e32 v61, 0xffff0000, v185
	v_lshl_add_u64 v[42:43], v[38:39], 0, v[18:19]
	global_load_dwordx2 v[64:65], v[42:43], off
	v_lshl_add_u64 v[42:43], v[38:39], 0, v[20:21]
	v_lshl_add_u64 v[44:45], v[38:39], 0, v[22:23]
	v_lshl_add_u64 v[46:47], v[38:39], 0, v[24:25]
	v_lshl_add_u64 v[68:69], v[38:39], 0, v[26:27]
	v_lshl_add_u64 v[70:71], v[38:39], 0, v[28:29]
	v_lshl_add_u64 v[74:75], v[38:39], 0, v[30:31]
	v_lshl_add_u64 v[38:39], v[38:39], 0, v[32:33]
	global_load_dwordx2 v[58:59], v[42:43], off
	global_load_dwordx2 v[52:53], v[44:45], off
	global_load_dwordx2 v[48:49], v[46:47], off
	s_nop 0
	global_load_dwordx2 v[46:47], v[68:69], off
	global_load_dwordx2 v[44:45], v[70:71], off
	global_load_dwordx2 v[42:43], v[74:75], off
	s_nop 0
	global_load_dwordx2 v[38:39], v[38:39], off
	s_waitcnt vmcnt(10)
	v_pk_mul_f32 v[68:69], v[6:7], v[66:67]
	v_pk_mul_f32 v[70:71], v[4:5], v[50:51]
	v_pk_fma_f32 v[62:63], v[2:3], v[62:63], v[68:69]
	v_pk_fma_f32 v[54:55], v[0:1], v[54:55], v[70:71]
	s_xor_b64 s[12:13], s[12:13], -1
	s_waitcnt vmcnt(9)
	v_pk_fma_f32 v[54:55], v[8:9], v[56:57], v[54:55]
	v_pk_fma_f32 v[68:69], v[10:11], v[60:61], v[62:63]
	v_cndmask_b32_e64 v73, 0, 1, s[12:13]
	v_cmp_ne_u32_e64 s[10:11], 1, v73
	s_andn2_b64 vcc, exec, s[12:13]
	s_waitcnt vmcnt(7)
	v_lshlrev_b32_e32 v62, 16, v64
	v_and_b32_e32 v63, 0xffff0000, v64
	v_lshlrev_b32_e32 v64, 16, v65
	v_and_b32_e32 v65, 0xffff0000, v65
	v_pk_fma_f32 v[70:71], v[14:15], v[64:65], v[68:69]
	v_pk_fma_f32 v[54:55], v[12:13], v[62:63], v[54:55]
	v_mul_f32_e32 v74, 0xbfb8aa3b, v70
	v_mul_f32_e32 v69, 0xbfb8aa3b, v54
	v_mul_f32_e32 v73, 0xbfb8aa3b, v55
	v_mul_f32_e32 v75, 0xbfb8aa3b, v71
	v_mov_b32_e32 v68, v54
	v_exp_f32_e32 v54, v69
	v_exp_f32_e32 v69, v73
	v_exp_f32_e32 v73, v74
	v_exp_f32_e32 v74, v75
	v_add_f32_e32 v54, 1.0, v54
	v_add_f32_e32 v69, 1.0, v69
	v_add_f32_e32 v73, 1.0, v73
	v_add_f32_e32 v77, 1.0, v74
	v_rcp_f32_e32 v74, v54
	v_rcp_f32_e32 v76, v69
	v_rcp_f32_e32 v75, v73
	v_rcp_f32_e32 v77, v77
	v_mov_b32_e32 v69, v70
	v_mov_b32_e32 v70, v55
	v_pk_mul_f32 v[68:69], v[68:69], v[74:75]
	v_pk_mul_f32 v[70:71], v[70:71], v[76:77]
	s_cbranch_vccnz .LBB0_239
	v_pk_mul_f32 v[54:55], v[70:71], v[70:71]
	s_nop 0
	v_pk_fma_f32 v[54:55], v[68:69], v[68:69], v[54:55]
	s_nop 0
	v_add_f32_e32 v54, v54, v55
	s_nop 1
	v_add_f32_dpp v54, v54, v54 quad_perm:[1,0,3,2] row_mask:0xf bank_mask:0xf
	s_nop 1
	v_add_f32_dpp v54, v54, v54 quad_perm:[2,3,0,1] row_mask:0xf bank_mask:0xf
	s_nop 1
	v_add_f32_dpp v54, v54, v54 row_half_mirror row_mask:0xf bank_mask:0xf
	s_nop 1
	v_add_f32_dpp v54, v54, v54 row_mirror row_mask:0xf bank_mask:0xf
	s_nop 0
	v_readlane_b32 s98, v54, 0
	v_readlane_b32 s99, v54, 16
	v_readlane_b32 s100, v54, 32
	v_readlane_b32 s101, v54, 48
	s_mov_b32 vcc_lo, 0
	s_mov_b32 vcc_hi, -1
	v_mov_b32_e32 v54, s98
	v_mov_b32_e32 v55, s100
	v_add_f32_e32 v54, s99, v54
	v_add_f32_e32 v55, s101, v55
	v_cndmask_b32_e32 v54, v54, v55, vcc
	v_add_f32_e32 v54, 0x358637bd, v54
	v_mul_f32_e32 v55, 0x4b800000, v54
	v_cmp_gt_f32_e32 vcc, s46, v54
	s_nop 1
	v_cndmask_b32_e32 v54, v54, v55, vcc
	v_rsq_f32_e32 v73, v54
	v_mov_b32_e32 v54, v68
	v_mov_b32_e32 v55, v70
	v_mov_b32_e32 v70, v69
	v_mul_f32_e32 v68, 0x45800000, v73
	v_cndmask_b32_e32 v68, v73, v68, vcc
	v_pk_mul_f32 v[74:75], v[70:71], v[68:69] op_sel_hi:[1,0]
	v_pk_mul_f32 v[68:69], v[54:55], v[68:69] op_sel_hi:[1,0]
	v_mov_b32_e32 v71, v75
	v_mov_b32_e32 v70, v69
	v_mov_b32_e32 v69, v74
.LBB0_239:
	v_pk_mul_f32 v[74:75], v[4:5], v[56:57]
	v_add_u32_e32 v73, s37, v86
	v_pk_fma_f32 v[50:51], v[0:1], v[50:51], v[74:75]
	s_waitcnt vmcnt(6)
	v_lshlrev_b32_e32 v54, 16, v58
	v_and_b32_e32 v55, 0xffff0000, v58
	v_cvt_pk_bf16_f32 v68, v68, v70
	v_cvt_pk_bf16_f32 v69, v69, v71
	v_add_u32_e32 v70, v73, v93
	v_pk_fma_f32 v[50:51], v[8:9], v[62:63], v[50:51]
	ds_write_b64 v70, v[68:69]
	v_pk_mul_f32 v[68:69], v[6:7], v[60:61]
	v_pk_fma_f32 v[50:51], v[12:13], v[54:55], v[50:51]
	v_pk_fma_f32 v[66:67], v[2:3], v[66:67], v[68:69]
	v_mul_f32_e32 v68, 0xbfb8aa3b, v50
	v_exp_f32_e32 v71, v68
	v_mul_f32_e32 v68, 0xbfb8aa3b, v51
	v_exp_f32_e32 v74, v68
	v_lshlrev_b32_e32 v58, 16, v59
	v_and_b32_e32 v59, 0xffff0000, v59
	v_pk_fma_f32 v[66:67], v[10:11], v[64:65], v[66:67]
	v_mov_b32_e32 v76, v50
	v_pk_fma_f32 v[68:69], v[14:15], v[58:59], v[66:67]
	v_add_f32_e32 v66, 1.0, v71
	v_add_f32_e32 v67, 1.0, v74
	v_mul_f32_e32 v71, 0xbfb8aa3b, v68
	v_mul_f32_e32 v74, 0xbfb8aa3b, v69
	v_exp_f32_e32 v71, v71
	v_exp_f32_e32 v75, v74
	v_rcp_f32_e32 v74, v67
	v_rcp_f32_e32 v66, v66
	v_add_f32_e32 v67, 1.0, v71
	v_add_f32_e32 v71, 1.0, v75
	v_rcp_f32_e32 v67, v67
	v_rcp_f32_e32 v75, v71
	v_mov_b32_e32 v77, v68
	v_mov_b32_e32 v68, v51
	v_pk_mul_f32 v[66:67], v[76:77], v[66:67]
	s_and_b64 vcc, exec, s[10:11]
	v_pk_mul_f32 v[68:69], v[68:69], v[74:75]
	s_cbranch_vccnz .LBB0_241
	v_pk_mul_f32 v[50:51], v[68:69], v[68:69]
	s_nop 0
	v_pk_fma_f32 v[50:51], v[66:67], v[66:67], v[50:51]
	s_nop 0
	v_add_f32_e32 v50, v50, v51
	s_nop 1
	v_add_f32_dpp v50, v50, v50 quad_perm:[1,0,3,2] row_mask:0xf bank_mask:0xf
	s_nop 1
	v_add_f32_dpp v50, v50, v50 quad_perm:[2,3,0,1] row_mask:0xf bank_mask:0xf
	s_nop 1
	v_add_f32_dpp v50, v50, v50 row_half_mirror row_mask:0xf bank_mask:0xf
	s_nop 1
	v_add_f32_dpp v50, v50, v50 row_mirror row_mask:0xf bank_mask:0xf
	s_nop 0
	v_readlane_b32 s98, v50, 0
	v_readlane_b32 s99, v50, 16
	v_readlane_b32 s100, v50, 32
	v_readlane_b32 s101, v50, 48
	s_mov_b32 vcc_lo, 0
	s_mov_b32 vcc_hi, -1
	v_mov_b32_e32 v50, s98
	v_mov_b32_e32 v51, s100
	v_add_f32_e32 v50, s99, v50
	v_add_f32_e32 v51, s101, v51
	v_cndmask_b32_e32 v50, v50, v51, vcc
	v_add_f32_e32 v50, 0x358637bd, v50
	v_mul_f32_e32 v51, 0x4b800000, v50
	v_cmp_gt_f32_e32 vcc, s46, v50
	s_nop 1
	v_cndmask_b32_e32 v50, v50, v51, vcc
	v_rsq_f32_e32 v71, v50
	v_mov_b32_e32 v50, v66
	v_mov_b32_e32 v51, v68
	v_mov_b32_e32 v68, v67
	v_mul_f32_e32 v66, 0x45800000, v71
	v_cndmask_b32_e32 v66, v71, v66, vcc
	v_pk_mul_f32 v[74:75], v[68:69], v[66:67] op_sel_hi:[1,0]
	v_pk_mul_f32 v[66:67], v[50:51], v[66:67] op_sel_hi:[1,0]
	v_mov_b32_e32 v69, v75
	v_mov_b32_e32 v68, v67
	v_mov_b32_e32 v67, v74
; #define LAS __attribute__((address_space(3)))
; DI unsigned pk2(float a, float b) { f32x2 v = {a, b}; nbf2 r = __builtin_convertvector(v, nbf2); return __builtin_bit_cast(unsigned, r); }
; DI float silu_f(float x) { return x * __builtin_amdgcn_rcpf(1.f + __expf(-x)); }
; DI void dprep_item(LAS unsigned char* ldsh, const Args& a, int l, int item, int tl) {
;     ...
;           for (int j = 0; j < 8; ++j) { f32x4 o = w[0] * xin[j] + w[1] * xin[j + 1] + w[2] * xin[j + 2] + w[3] * xin[j + 3];
;               o[0] = silu_f(o[0]); o[1] = silu_f(o[1]); o[2] = silu_f(o[2]); o[3] = silu_f(o[3]);
;               if (sec < 2) { float ss = (o[0] * o[0] + o[1] * o[1]) + (o[2] * o[2] + o[3] * o[3]);
;                   ss += __shfl_xor(ss, 16); ss += __shfl_xor(ss, 8); ss += __shfl_xor(ss, 4); ss += __shfl_xor(ss, 2); ss += __shfl_xor(ss, 1);
;                   const float sc = rsqrtf(ss + 1e-6f) * (sec == 0 ? 0.08838834764831845f : 1.f); o = o * sc; }
;               u32x2 pw; pw.x = pk2(o[0], o[1]); pw.y = pk2(o[2], o[3]); *(LAS u32x2*)(dst + (rg * 8 + j) * 136 + c0) = pw; }
.LBB0_241:
	v_cvt_pk_bf16_f32 v66, v66, v68
	v_cvt_pk_bf16_f32 v67, v67, v69
	ds_write_b64 v70, v[66:67] offset:272
	v_pk_mul_f32 v[66:67], v[6:7], v[64:65]
	v_pk_mul_f32 v[68:69], v[4:5], v[62:63]
	v_pk_fma_f32 v[60:61], v[2:3], v[60:61], v[66:67]
	v_pk_fma_f32 v[56:57], v[0:1], v[56:57], v[68:69]
	s_waitcnt vmcnt(5)
	v_lshlrev_b32_e32 v50, 16, v52
	v_and_b32_e32 v51, 0xffff0000, v52
	v_lshlrev_b32_e32 v52, 16, v53
	v_and_b32_e32 v53, 0xffff0000, v53
	v_pk_fma_f32 v[60:61], v[10:11], v[58:59], v[60:61]
	v_pk_fma_f32 v[56:57], v[8:9], v[54:55], v[56:57]
	v_pk_fma_f32 v[60:61], v[14:15], v[52:53], v[60:61]
	v_pk_fma_f32 v[56:57], v[12:13], v[50:51], v[56:57]
	v_mul_f32_e32 v68, 0xbfb8aa3b, v60
	v_mul_f32_e32 v67, 0xbfb8aa3b, v57
	v_mul_f32_e32 v66, 0xbfb8aa3b, v56
	v_exp_f32_e32 v67, v67
	v_exp_f32_e32 v69, v68
	v_mul_f32_e32 v68, 0xbfb8aa3b, v61
	v_exp_f32_e32 v66, v66
	v_exp_f32_e32 v71, v68
	v_add_f32_e32 v67, 1.0, v67
	v_rcp_f32_e32 v68, v67
	v_add_f32_e32 v66, 1.0, v66
	v_add_f32_e32 v67, 1.0, v69
	v_add_f32_e32 v69, 1.0, v71
	v_rcp_f32_e32 v66, v66
	v_rcp_f32_e32 v67, v67
	v_rcp_f32_e32 v69, v69
	v_mov_b32_e32 v74, v56
	v_mov_b32_e32 v75, v60
	v_mov_b32_e32 v60, v57
	v_pk_mul_f32 v[66:67], v[74:75], v[66:67]
	s_and_b64 vcc, exec, s[10:11]
	v_pk_mul_f32 v[68:69], v[60:61], v[68:69]
	s_cbranch_vccnz .LBB0_243
	v_pk_mul_f32 v[56:57], v[68:69], v[68:69]
	s_nop 0
	v_pk_fma_f32 v[56:57], v[66:67], v[66:67], v[56:57]
	s_nop 0
	v_add_f32_e32 v56, v56, v57
	s_nop 1
	v_add_f32_dpp v56, v56, v56 quad_perm:[1,0,3,2] row_mask:0xf bank_mask:0xf
	s_nop 1
	v_add_f32_dpp v56, v56, v56 quad_perm:[2,3,0,1] row_mask:0xf bank_mask:0xf
	s_nop 1
	v_add_f32_dpp v56, v56, v56 row_half_mirror row_mask:0xf bank_mask:0xf
	s_nop 1
	v_add_f32_dpp v56, v56, v56 row_mirror row_mask:0xf bank_mask:0xf
	s_nop 0
	v_readlane_b32 s98, v56, 0
	v_readlane_b32 s99, v56, 16
	v_readlane_b32 s100, v56, 32
	v_readlane_b32 s101, v56, 48
	s_mov_b32 vcc_lo, 0
	s_mov_b32 vcc_hi, -1
	v_mov_b32_e32 v56, s98
	v_mov_b32_e32 v57, s100
	v_add_f32_e32 v56, s99, v56
	v_add_f32_e32 v57, s101, v57
	v_cndmask_b32_e32 v56, v56, v57, vcc
	v_add_f32_e32 v56, 0x358637bd, v56
	v_mul_f32_e32 v57, 0x4b800000, v56
	v_cmp_gt_f32_e32 vcc, s46, v56
	s_nop 1
	v_cndmask_b32_e32 v56, v56, v57, vcc
	v_rsq_f32_e32 v60, v56
	v_mov_b32_e32 v56, v66
	v_mov_b32_e32 v57, v68
	v_mov_b32_e32 v68, v67
	v_mul_f32_e32 v61, 0x45800000, v60
	v_cndmask_b32_e32 v60, v60, v61, vcc
	v_pk_mul_f32 v[74:75], v[68:69], v[60:61] op_sel_hi:[1,0]
	v_pk_mul_f32 v[66:67], v[56:57], v[60:61] op_sel_hi:[1,0]
	v_mov_b32_e32 v69, v75
	v_mov_b32_e32 v68, v67
	v_mov_b32_e32 v67, v74
.LBB0_243:
	s_waitcnt vmcnt(4)
	v_lshlrev_b32_e32 v56, 16, v48
	v_and_b32_e32 v57, 0xffff0000, v48
	v_lshlrev_b32_e32 v60, 16, v49
	v_and_b32_e32 v61, 0xffff0000, v49
	v_cvt_pk_bf16_f32 v48, v66, v68
	v_cvt_pk_bf16_f32 v49, v67, v69
	ds_write_b64 v70, v[48:49] offset:544
	v_pk_mul_f32 v[48:49], v[6:7], v[58:59]
	v_pk_mul_f32 v[66:67], v[4:5], v[54:55]
	v_pk_fma_f32 v[48:49], v[2:3], v[64:65], v[48:49]
	v_pk_fma_f32 v[62:63], v[0:1], v[62:63], v[66:67]
	v_pk_fma_f32 v[48:49], v[10:11], v[52:53], v[48:49]
	v_pk_fma_f32 v[62:63], v[8:9], v[50:51], v[62:63]
	v_pk_fma_f32 v[48:49], v[14:15], v[60:61], v[48:49]
	v_pk_fma_f32 v[64:65], v[12:13], v[56:57], v[62:63]
	v_mul_f32_e32 v66, 0xbfb8aa3b, v48
	v_mul_f32_e32 v63, 0xbfb8aa3b, v65
	v_mul_f32_e32 v62, 0xbfb8aa3b, v64
	v_exp_f32_e32 v63, v63
	v_exp_f32_e32 v67, v66
	v_mul_f32_e32 v66, 0xbfb8aa3b, v49
	v_exp_f32_e32 v62, v62
	v_exp_f32_e32 v68, v66
	v_add_f32_e32 v63, 1.0, v63
	v_rcp_f32_e32 v66, v63
	v_add_f32_e32 v62, 1.0, v62
	v_add_f32_e32 v63, 1.0, v67
	v_add_f32_e32 v67, 1.0, v68
	v_rcp_f32_e32 v62, v62
	v_rcp_f32_e32 v63, v63
	v_rcp_f32_e32 v67, v67
	v_mov_b32_e32 v68, v64
	v_mov_b32_e32 v69, v48
	v_mov_b32_e32 v48, v65
	v_pk_mul_f32 v[62:63], v[68:69], v[62:63]
	s_and_b64 vcc, exec, s[10:11]
	v_pk_mul_f32 v[64:65], v[48:49], v[66:67]
	s_cbranch_vccnz .LBB0_245
	v_pk_mul_f32 v[48:49], v[64:65], v[64:65]
	s_nop 0
	v_pk_fma_f32 v[48:49], v[62:63], v[62:63], v[48:49]
	s_nop 0
	v_add_f32_e32 v48, v48, v49
	s_nop 1
	v_add_f32_dpp v48, v48, v48 quad_perm:[1,0,3,2] row_mask:0xf bank_mask:0xf
	s_nop 1
	v_add_f32_dpp v48, v48, v48 quad_perm:[2,3,0,1] row_mask:0xf bank_mask:0xf
	s_nop 1
	v_add_f32_dpp v48, v48, v48 row_half_mirror row_mask:0xf bank_mask:0xf
	s_nop 1
	v_add_f32_dpp v48, v48, v48 row_mirror row_mask:0xf bank_mask:0xf
	s_nop 0
	v_readlane_b32 s98, v48, 0
	v_readlane_b32 s99, v48, 16
	v_readlane_b32 s100, v48, 32
	v_readlane_b32 s101, v48, 48
	s_mov_b32 vcc_lo, 0
	s_mov_b32 vcc_hi, -1
	v_mov_b32_e32 v48, s98
	v_mov_b32_e32 v49, s100
	v_add_f32_e32 v48, s99, v48
	v_add_f32_e32 v49, s101, v49
	v_cndmask_b32_e32 v48, v48, v49, vcc
	v_add_f32_e32 v48, 0x358637bd, v48
	v_mul_f32_e32 v49, 0x4b800000, v48
	v_cmp_gt_f32_e32 vcc, s46, v48
	s_nop 1
	v_cndmask_b32_e32 v48, v48, v49, vcc
	v_rsq_f32_e32 v66, v48
	v_mov_b32_e32 v48, v62
	v_mov_b32_e32 v49, v64
	v_mov_b32_e32 v64, v63
	v_mul_f32_e32 v62, 0x45800000, v66
	v_cndmask_b32_e32 v62, v66, v62, vcc
	v_pk_mul_f32 v[66:67], v[64:65], v[62:63] op_sel_hi:[1,0]
	v_pk_mul_f32 v[62:63], v[48:49], v[62:63] op_sel_hi:[1,0]
	v_mov_b32_e32 v65, v67
	v_mov_b32_e32 v64, v63
	v_mov_b32_e32 v63, v66
; #define LAS __attribute__((address_space(3)))
; DI unsigned pk2(float a, float b) { f32x2 v = {a, b}; nbf2 r = __builtin_convertvector(v, nbf2); return __builtin_bit_cast(unsigned, r); }
; DI float silu_f(float x) { return x * __builtin_amdgcn_rcpf(1.f + __expf(-x)); }
; DI void dprep_item(LAS unsigned char* ldsh, const Args& a, int l, int item, int tl) {
;     ...
;           for (int j = 0; j < 8; ++j) { f32x4 o = w[0] * xin[j] + w[1] * xin[j + 1] + w[2] * xin[j + 2] + w[3] * xin[j + 3];
;               o[0] = silu_f(o[0]); o[1] = silu_f(o[1]); o[2] = silu_f(o[2]); o[3] = silu_f(o[3]);
;               if (sec < 2) { float ss = (o[0] * o[0] + o[1] * o[1]) + (o[2] * o[2] + o[3] * o[3]);
;                   ss += __shfl_xor(ss, 16); ss += __shfl_xor(ss, 8); ss += __shfl_xor(ss, 4); ss += __shfl_xor(ss, 2); ss += __shfl_xor(ss, 1);
;                   const float sc = rsqrtf(ss + 1e-6f) * (sec == 0 ? 0.08838834764831845f : 1.f); o = o * sc; }
;               u32x2 pw; pw.x = pk2(o[0], o[1]); pw.y = pk2(o[2], o[3]); *(LAS u32x2*)(dst + (rg * 8 + j) * 136 + c0) = pw; }
.LBB0_245:
	v_cvt_pk_bf16_f32 v62, v62, v64
	v_cvt_pk_bf16_f32 v63, v63, v65
	v_pk_mul_f32 v[64:65], v[4:5], v[50:51]
	s_waitcnt vmcnt(3)
	v_lshlrev_b32_e32 v48, 16, v46
	v_pk_fma_f32 v[54:55], v[0:1], v[54:55], v[64:65]
	v_and_b32_e32 v49, 0xffff0000, v46
	v_pk_fma_f32 v[54:55], v[8:9], v[56:57], v[54:55]
	ds_write_b64 v70, v[62:63] offset:816
	v_pk_mul_f32 v[62:63], v[6:7], v[52:53]
	v_pk_fma_f32 v[54:55], v[12:13], v[48:49], v[54:55]
	v_pk_fma_f32 v[58:59], v[2:3], v[58:59], v[62:63]
	v_mul_f32_e32 v62, 0xbfb8aa3b, v54
	v_exp_f32_e32 v64, v62
	v_mul_f32_e32 v62, 0xbfb8aa3b, v55
	v_exp_f32_e32 v65, v62
	v_lshlrev_b32_e32 v46, 16, v47
	v_and_b32_e32 v47, 0xffff0000, v47
	v_pk_fma_f32 v[58:59], v[10:11], v[60:61], v[58:59]
	s_and_b64 vcc, exec, s[10:11]
	v_pk_fma_f32 v[62:63], v[14:15], v[46:47], v[58:59]
	v_add_f32_e32 v58, 1.0, v64
	v_mul_f32_e32 v64, 0xbfb8aa3b, v62
	v_add_f32_e32 v59, 1.0, v65
	v_exp_f32_e32 v65, v64
	v_mul_f32_e32 v64, 0xbfb8aa3b, v63
	v_exp_f32_e32 v66, v64
	v_rcp_f32_e32 v64, v59
	v_add_f32_e32 v59, 1.0, v65
	v_rcp_f32_e32 v58, v58
	v_add_f32_e32 v65, 1.0, v66
	v_rcp_f32_e32 v59, v59
	v_rcp_f32_e32 v65, v65
	v_mov_b32_e32 v66, v54
	v_mov_b32_e32 v67, v62
	v_mov_b32_e32 v62, v55
	v_pk_mul_f32 v[58:59], v[66:67], v[58:59]
	v_pk_mul_f32 v[62:63], v[62:63], v[64:65]
	s_cbranch_vccnz .LBB0_247
	v_pk_mul_f32 v[54:55], v[62:63], v[62:63]
	s_nop 0
	v_pk_fma_f32 v[54:55], v[58:59], v[58:59], v[54:55]
	s_nop 0
	v_add_f32_e32 v54, v54, v55
	s_nop 1
	v_add_f32_dpp v54, v54, v54 quad_perm:[1,0,3,2] row_mask:0xf bank_mask:0xf
	s_nop 1
	v_add_f32_dpp v54, v54, v54 quad_perm:[2,3,0,1] row_mask:0xf bank_mask:0xf
	s_nop 1
	v_add_f32_dpp v54, v54, v54 row_half_mirror row_mask:0xf bank_mask:0xf
	s_nop 1
	v_add_f32_dpp v54, v54, v54 row_mirror row_mask:0xf bank_mask:0xf
	s_nop 0
	v_readlane_b32 s98, v54, 0
	v_readlane_b32 s99, v54, 16
	v_readlane_b32 s100, v54, 32
	v_readlane_b32 s101, v54, 48
	s_mov_b32 vcc_lo, 0
	s_mov_b32 vcc_hi, -1
	v_mov_b32_e32 v54, s98
	v_mov_b32_e32 v55, s100
	v_add_f32_e32 v54, s99, v54
	v_add_f32_e32 v55, s101, v55
	v_cndmask_b32_e32 v54, v54, v55, vcc
	v_add_f32_e32 v54, 0x358637bd, v54
	v_mul_f32_e32 v55, 0x4b800000, v54
	v_cmp_gt_f32_e32 vcc, s46, v54
	s_nop 1
	v_cndmask_b32_e32 v54, v54, v55, vcc
	v_rsq_f32_e32 v64, v54
	v_mov_b32_e32 v54, v58
	v_mov_b32_e32 v55, v62
	v_mov_b32_e32 v62, v59
	v_mul_f32_e32 v58, 0x45800000, v64
	v_cndmask_b32_e32 v58, v64, v58, vcc
	v_pk_mul_f32 v[64:65], v[62:63], v[58:59] op_sel_hi:[1,0]
	v_pk_mul_f32 v[58:59], v[54:55], v[58:59] op_sel_hi:[1,0]
	v_mov_b32_e32 v63, v65
	v_mov_b32_e32 v62, v59
	v_mov_b32_e32 v59, v64
.LBB0_247:
	v_cvt_pk_bf16_f32 v58, v58, v62
	v_cvt_pk_bf16_f32 v59, v59, v63
	v_pk_mul_f32 v[62:63], v[4:5], v[56:57]
	s_waitcnt vmcnt(2)
	v_lshlrev_b32_e32 v54, 16, v44
	v_pk_fma_f32 v[50:51], v[0:1], v[50:51], v[62:63]
	v_and_b32_e32 v55, 0xffff0000, v44
	v_pk_fma_f32 v[50:51], v[8:9], v[48:49], v[50:51]
	ds_write_b64 v70, v[58:59] offset:1088
	v_pk_mul_f32 v[58:59], v[6:7], v[60:61]
	v_pk_fma_f32 v[50:51], v[12:13], v[54:55], v[50:51]
	v_pk_fma_f32 v[52:53], v[2:3], v[52:53], v[58:59]
	v_mul_f32_e32 v58, 0xbfb8aa3b, v50
	v_exp_f32_e32 v62, v58
	v_mul_f32_e32 v58, 0xbfb8aa3b, v51
	v_exp_f32_e32 v63, v58
	v_lshlrev_b32_e32 v44, 16, v45
	v_and_b32_e32 v45, 0xffff0000, v45
	v_pk_fma_f32 v[52:53], v[10:11], v[46:47], v[52:53]
	s_and_b64 vcc, exec, s[10:11]
	v_pk_fma_f32 v[58:59], v[14:15], v[44:45], v[52:53]
	v_add_f32_e32 v52, 1.0, v62
	v_mul_f32_e32 v62, 0xbfb8aa3b, v58
	v_add_f32_e32 v53, 1.0, v63
	v_exp_f32_e32 v63, v62
	v_mul_f32_e32 v62, 0xbfb8aa3b, v59
	v_exp_f32_e32 v64, v62
	v_rcp_f32_e32 v62, v53
	v_add_f32_e32 v53, 1.0, v63
	v_rcp_f32_e32 v52, v52
	v_add_f32_e32 v63, 1.0, v64
	v_rcp_f32_e32 v53, v53
	v_rcp_f32_e32 v63, v63
	v_mov_b32_e32 v64, v50
	v_mov_b32_e32 v65, v58
	v_mov_b32_e32 v58, v51
	v_pk_mul_f32 v[52:53], v[64:65], v[52:53]
	v_pk_mul_f32 v[58:59], v[58:59], v[62:63]
	s_cbranch_vccnz .LBB0_249
	v_pk_mul_f32 v[50:51], v[58:59], v[58:59]
	s_nop 0
	v_pk_fma_f32 v[50:51], v[52:53], v[52:53], v[50:51]
	s_nop 0
	v_add_f32_e32 v50, v50, v51
	s_nop 1
	v_add_f32_dpp v50, v50, v50 quad_perm:[1,0,3,2] row_mask:0xf bank_mask:0xf
	s_nop 1
	v_add_f32_dpp v50, v50, v50 quad_perm:[2,3,0,1] row_mask:0xf bank_mask:0xf
	s_nop 1
	v_add_f32_dpp v50, v50, v50 row_half_mirror row_mask:0xf bank_mask:0xf
	s_nop 1
	v_add_f32_dpp v50, v50, v50 row_mirror row_mask:0xf bank_mask:0xf
	s_nop 0
	v_readlane_b32 s98, v50, 0
	v_readlane_b32 s99, v50, 16
	v_readlane_b32 s100, v50, 32
	v_readlane_b32 s101, v50, 48
	s_mov_b32 vcc_lo, 0
	s_mov_b32 vcc_hi, -1
	v_mov_b32_e32 v50, s98
	v_mov_b32_e32 v51, s100
	v_add_f32_e32 v50, s99, v50
	v_add_f32_e32 v51, s101, v51
	v_cndmask_b32_e32 v50, v50, v51, vcc
	v_add_f32_e32 v50, 0x358637bd, v50
	v_mul_f32_e32 v51, 0x4b800000, v50
	v_cmp_gt_f32_e32 vcc, s46, v50
	s_nop 1
	v_cndmask_b32_e32 v50, v50, v51, vcc
	v_rsq_f32_e32 v62, v50
	v_mov_b32_e32 v50, v52
	v_mov_b32_e32 v51, v58
	v_mov_b32_e32 v58, v53
	v_mul_f32_e32 v52, 0x45800000, v62
	v_cndmask_b32_e32 v52, v62, v52, vcc
	v_pk_mul_f32 v[62:63], v[58:59], v[52:53] op_sel_hi:[1,0]
	v_pk_mul_f32 v[52:53], v[50:51], v[52:53] op_sel_hi:[1,0]
	v_mov_b32_e32 v59, v63
	v_mov_b32_e32 v58, v53
	v_mov_b32_e32 v53, v62
; #define LAS __attribute__((address_space(3)))
; DI unsigned pk2(float a, float b) { f32x2 v = {a, b}; nbf2 r = __builtin_convertvector(v, nbf2); return __builtin_bit_cast(unsigned, r); }
; DI float silu_f(float x) { return x * __builtin_amdgcn_rcpf(1.f + __expf(-x)); }
; DI void dprep_item(LAS unsigned char* ldsh, const Args& a, int l, int item, int tl) {
;     ...
;           for (int j = 0; j < 8; ++j) { f32x4 o = w[0] * xin[j] + w[1] * xin[j + 1] + w[2] * xin[j + 2] + w[3] * xin[j + 3];
;               o[0] = silu_f(o[0]); o[1] = silu_f(o[1]); o[2] = silu_f(o[2]); o[3] = silu_f(o[3]);
;               if (sec < 2) { float ss = (o[0] * o[0] + o[1] * o[1]) + (o[2] * o[2] + o[3] * o[3]);
;                   ss += __shfl_xor(ss, 16); ss += __shfl_xor(ss, 8); ss += __shfl_xor(ss, 4); ss += __shfl_xor(ss, 2); ss += __shfl_xor(ss, 1);
;                   const float sc = rsqrtf(ss + 1e-6f) * (sec == 0 ? 0.08838834764831845f : 1.f); o = o * sc; }
;               u32x2 pw; pw.x = pk2(o[0], o[1]); pw.y = pk2(o[2], o[3]); *(LAS u32x2*)(dst + (rg * 8 + j) * 136 + c0) = pw; }
.LBB0_249:
	v_cvt_pk_bf16_f32 v52, v52, v58
	v_cvt_pk_bf16_f32 v53, v53, v59
	v_pk_mul_f32 v[58:59], v[4:5], v[48:49]
	s_waitcnt vmcnt(1)
	v_lshlrev_b32_e32 v50, 16, v42
	v_pk_fma_f32 v[56:57], v[0:1], v[56:57], v[58:59]
	v_and_b32_e32 v51, 0xffff0000, v42
	v_pk_fma_f32 v[56:57], v[8:9], v[54:55], v[56:57]
	ds_write_b64 v70, v[52:53] offset:1360
	v_pk_fma_f32 v[56:57], v[12:13], v[50:51], v[56:57]
	v_pk_mul_f32 v[52:53], v[6:7], v[46:47]
	v_mul_f32_e32 v58, 0xbfb8aa3b, v56
	v_pk_fma_f32 v[52:53], v[2:3], v[60:61], v[52:53]
	v_exp_f32_e32 v60, v58
	v_mul_f32_e32 v58, 0xbfb8aa3b, v57
	v_exp_f32_e32 v61, v58
	v_lshlrev_b32_e32 v42, 16, v43
	v_and_b32_e32 v43, 0xffff0000, v43
	v_pk_fma_f32 v[52:53], v[10:11], v[44:45], v[52:53]
	s_and_b64 vcc, exec, s[10:11]
	v_pk_fma_f32 v[58:59], v[14:15], v[42:43], v[52:53]
	v_add_f32_e32 v52, 1.0, v60
	v_mul_f32_e32 v60, 0xbfb8aa3b, v58
	v_add_f32_e32 v53, 1.0, v61
	v_exp_f32_e32 v61, v60
	v_mul_f32_e32 v60, 0xbfb8aa3b, v59
	v_exp_f32_e32 v62, v60
	v_rcp_f32_e32 v60, v53
	v_add_f32_e32 v53, 1.0, v61
	v_rcp_f32_e32 v52, v52
	v_add_f32_e32 v61, 1.0, v62
	v_rcp_f32_e32 v53, v53
	v_rcp_f32_e32 v61, v61
	v_mov_b32_e32 v62, v56
	v_mov_b32_e32 v63, v58
	v_mov_b32_e32 v58, v57
	v_pk_mul_f32 v[52:53], v[62:63], v[52:53]
	v_pk_mul_f32 v[56:57], v[58:59], v[60:61]
	s_cbranch_vccnz .LBB0_251
	v_pk_mul_f32 v[58:59], v[56:57], v[56:57]
	s_nop 0
	v_pk_fma_f32 v[58:59], v[52:53], v[52:53], v[58:59]
	s_nop 0
	v_add_f32_e32 v58, v58, v59
	s_nop 1
	v_add_f32_dpp v58, v58, v58 quad_perm:[1,0,3,2] row_mask:0xf bank_mask:0xf
	s_nop 1
	v_add_f32_dpp v58, v58, v58 quad_perm:[2,3,0,1] row_mask:0xf bank_mask:0xf
	s_nop 1
	v_add_f32_dpp v58, v58, v58 row_half_mirror row_mask:0xf bank_mask:0xf
	s_nop 1
	v_add_f32_dpp v58, v58, v58 row_mirror row_mask:0xf bank_mask:0xf
	s_nop 0
	v_readlane_b32 s98, v58, 0
	v_readlane_b32 s99, v58, 16
	v_readlane_b32 s100, v58, 32
	v_readlane_b32 s101, v58, 48
	s_mov_b32 vcc_lo, 0
	s_mov_b32 vcc_hi, -1
	v_mov_b32_e32 v58, s98
	v_mov_b32_e32 v59, s100
	v_add_f32_e32 v58, s99, v58
	v_add_f32_e32 v59, s101, v59
	v_cndmask_b32_e32 v58, v58, v59, vcc
	v_add_f32_e32 v58, 0x358637bd, v58
	v_mul_f32_e32 v59, 0x4b800000, v58
	v_cmp_gt_f32_e32 vcc, s46, v58
	s_nop 1
	v_cndmask_b32_e32 v58, v58, v59, vcc
	v_rsq_f32_e32 v60, v58
	v_mov_b32_e32 v58, v52
	v_mov_b32_e32 v59, v56
	v_mov_b32_e32 v56, v53
	v_mul_f32_e32 v52, 0x45800000, v60
	v_cndmask_b32_e32 v52, v60, v52, vcc
	v_pk_mul_f32 v[60:61], v[56:57], v[52:53] op_sel_hi:[1,0]
	v_pk_mul_f32 v[52:53], v[58:59], v[52:53] op_sel_hi:[1,0]
	v_mov_b32_e32 v57, v61
	v_mov_b32_e32 v56, v53
	v_mov_b32_e32 v53, v60

; #define LAS __attribute__((address_space(3)))
; DI const float* INP(const Args& a, int i) { asm volatile("" : "+s"(i)); return a.in[i]; }
; DI void ln_phase(LAS unsigned char* lds, const Args& a, int l, int mode) {
;     ...
;     const float* gam = INP(a, mode == 1 ? 5 : (mode == 2 ? 18 : 23)) + l * DM;
;     const float* bet = INP(a, mode == 1 ? 6 : (mode == 2 ? 19 : 24)) + l * DM;
;     LAS float* w8s = (LAS float*)lds;
;     if (mode == 1) { const float* win = INP(a, 10) + (size_t)l * DM * INDIM + 2048;
;         for (int i = tid; i < 8192; i += 512) { const int k = i >> 3, c = i & 7; w8s[c * 1024 + k] = win[(size_t)k * INDIM + c]; }
.LBB0_742:
	s_cmp_eq_u32 s2, 2
	s_cselect_b64 s[10:11], -1, 0
	s_and_b64 s[8:9], s[10:11], exec
	s_cselect_b32 s14, 18, 23
	s_cselect_b32 s15, 19, 24
	s_cmp_eq_u32 s2, 1
	s_cselect_b64 s[12:13], -1, 0
	s_and_b64 s[8:9], s[12:13], exec
	v_mov_b32_e32 v32, v152
	s_cselect_b32 s8, 5, s14
	s_cselect_b32 s14, 6, s15
	s_ashr_i32 s9, s8, 31
	s_lshl_b64 s[8:9], s[8:9], 3
	s_add_u32 s8, s0, s8
	s_addc_u32 s9, s1, s9
	s_ashr_i32 s15, s14, 31
	s_lshl_b64 s[14:15], s[14:15], 3
	s_add_u32 s16, s0, s14
	s_addc_u32 s17, s1, s15
	s_load_dwordx2 s[14:15], s[8:9], 0x0
	s_nop 0
	s_load_dwordx2 s[8:9], s[16:17], 0x0
	s_cmp_lg_u32 s2, 1
	s_cbranch_scc1 .LBB0_756
	s_mov_b32 s18, 10
	v_cmp_gt_i32_e32 vcc, s93, v32
	s_and_saveexec_b64 s[16:17], vcc
	s_cbranch_execz .LBB0_755
	s_load_dwordx2 s[18:19], s[0:1], 0x50
	s_mul_i32 s29, s25, 0xa08000
	s_mul_hi_i32 s28, s25, 0xa08000
	s_waitcnt vmcnt(0)
	v_and_b32_e32 v2, 7, v32
	v_lshlrev_b32_e32 v128, 2, v2
	v_lshl_add_u32 v4, v2, 12, 0
	v_lshrrev_b32_e32 v3, 3, v32
	v_lshl_add_u32 v4, v3, 2, v4
	s_waitcnt lgkmcnt(0)
	s_add_u32 s18, s18, s29
	s_addc_u32 s19, s19, s28
	v_lshl_add_u64 v[0:1], s[18:19], 0, v[128:129]
	v_lshl_add_u64 v[0:1], v[0:1], 0, s[26:27]
	s_movk_i32 s38, 0x2820
	v_mad_u64_u32 v[0:1], s[36:37], v3, s38, v[0:1]
	s_mov_b64 s[28:29], 0xa0800
	global_load_dword v16, v[0:1], off
	v_lshl_add_u64 v[0:1], v[0:1], 0, s[28:29]
	global_load_dword v17, v[0:1], off
	v_lshl_add_u64 v[0:1], v[0:1], 0, s[28:29]
	global_load_dword v18, v[0:1], off
	v_lshl_add_u64 v[0:1], v[0:1], 0, s[28:29]
	global_load_dword v19, v[0:1], off
	v_lshl_add_u64 v[0:1], v[0:1], 0, s[28:29]
	global_load_dword v20, v[0:1], off
	v_lshl_add_u64 v[0:1], v[0:1], 0, s[28:29]
	global_load_dword v21, v[0:1], off
	v_lshl_add_u64 v[0:1], v[0:1], 0, s[28:29]
	global_load_dword v22, v[0:1], off
	v_lshl_add_u64 v[0:1], v[0:1], 0, s[28:29]
	global_load_dword v23, v[0:1], off
	v_lshl_add_u64 v[0:1], v[0:1], 0, s[28:29]
	global_load_dword v24, v[0:1], off
	v_lshl_add_u64 v[0:1], v[0:1], 0, s[28:29]
	global_load_dword v25, v[0:1], off
	v_lshl_add_u64 v[0:1], v[0:1], 0, s[28:29]
	global_load_dword v26, v[0:1], off
	v_lshl_add_u64 v[0:1], v[0:1], 0, s[28:29]
	global_load_dword v27, v[0:1], off
	v_lshl_add_u64 v[0:1], v[0:1], 0, s[28:29]
	global_load_dword v28, v[0:1], off
	v_lshl_add_u64 v[0:1], v[0:1], 0, s[28:29]
	global_load_dword v29, v[0:1], off
	v_lshl_add_u64 v[0:1], v[0:1], 0, s[28:29]
	global_load_dword v30, v[0:1], off
	v_lshl_add_u64 v[0:1], v[0:1], 0, s[28:29]
	global_load_dword v31, v[0:1], off
	s_waitcnt vmcnt(15)
	ds_write_b32 v4, v16
	s_waitcnt vmcnt(14)
	ds_write_b32 v4, v17 offset:256
	s_waitcnt vmcnt(13)
	ds_write_b32 v4, v18 offset:512
	s_waitcnt vmcnt(12)
	ds_write_b32 v4, v19 offset:768
	s_waitcnt vmcnt(11)
	ds_write_b32 v4, v20 offset:1024
	s_waitcnt vmcnt(10)
	ds_write_b32 v4, v21 offset:1280
	s_waitcnt vmcnt(9)
	ds_write_b32 v4, v22 offset:1536
	s_waitcnt vmcnt(8)
	ds_write_b32 v4, v23 offset:1792
	s_waitcnt vmcnt(7)
	ds_write_b32 v4, v24 offset:2048
	s_waitcnt vmcnt(6)
	ds_write_b32 v4, v25 offset:2304
	s_waitcnt vmcnt(5)
	ds_write_b32 v4, v26 offset:2560
	s_waitcnt vmcnt(4)
	ds_write_b32 v4, v27 offset:2816
	s_waitcnt vmcnt(3)
	ds_write_b32 v4, v28 offset:3072
	s_waitcnt vmcnt(2)
	ds_write_b32 v4, v29 offset:3328
	s_waitcnt vmcnt(1)
	ds_write_b32 v4, v30 offset:3584
	s_waitcnt vmcnt(0)
	ds_write_b32 v4, v31 offset:3840

; __global__ void __launch_bounds__(512) mk_fwd(Args a) {
;     extern __shared__ __attribute__((aligned(16))) unsigned char lds_raw[];
	.amdhsa_kernel _Z6mk_fwd4Args
		.amdhsa_group_segment_fixed_size 0
		.amdhsa_private_segment_fixed_size 0
		.amdhsa_kernarg_size 480
		.amdhsa_user_sgpr_count 2
		.amdhsa_user_sgpr_dispatch_ptr 0
		.amdhsa_user_sgpr_queue_ptr 0
		.amdhsa_user_sgpr_kernarg_segment_ptr 1
		.amdhsa_user_sgpr_dispatch_id 0
		.amdhsa_user_sgpr_kernarg_preload_length 0
		.amdhsa_user_sgpr_kernarg_preload_offset 0
		.amdhsa_user_sgpr_private_segment_size 0
		.amdhsa_uses_dynamic_stack 0
		.amdhsa_enable_private_segment 0
		.amdhsa_system_sgpr_workgroup_id_x 1
		.amdhsa_system_sgpr_workgroup_id_y 0
		.amdhsa_system_sgpr_workgroup_id_z 0
		.amdhsa_system_sgpr_workgroup_info 0
		.amdhsa_system_vgpr_workitem_id 2
		.amdhsa_next_free_vgpr 256
		.amdhsa_next_free_sgpr 102
		.amdhsa_accum_offset 256
		.amdhsa_reserve_vcc 1
		.amdhsa_float_round_mode_32 0
		.amdhsa_float_round_mode_16_64 0
		.amdhsa_float_denorm_mode_32 3
		.amdhsa_float_denorm_mode_16_64 3
		.amdhsa_dx10_clamp 1
		.amdhsa_ieee_mode 1
		.amdhsa_fp16_overflow 0
		.amdhsa_tg_split 0
		.amdhsa_exception_fp_ieee_invalid_op 0
		.amdhsa_exception_fp_denorm_src 0
		.amdhsa_exception_fp_ieee_div_zero 0
		.amdhsa_exception_fp_ieee_overflow 0
		.amdhsa_exception_fp_ieee_underflow 0
		.amdhsa_exception_fp_ieee_inexact 0
		.amdhsa_exception_int_div_zero 0
	.end_amdhsa_kernel

; __global__ void __launch_bounds__(512) mk_fwd(Args a) {
;     extern __shared__ __attribute__((aligned(16))) unsigned char lds_raw[];
amdhsa.kernels:
  - .agpr_count:     0
    .args:
      - .offset:         0
        .size:           224
        .value_kind:     by_value
      - .offset:         224
        .size:           4
        .value_kind:     hidden_block_count_x
      - .offset:         228
        .size:           4
        .value_kind:     hidden_block_count_y
      - .offset:         232
        .size:           4
        .value_kind:     hidden_block_count_z
      - .offset:         236
        .size:           2
        .value_kind:     hidden_group_size_x
      - .offset:         238
        .size:           2
        .value_kind:     hidden_group_size_y
      - .offset:         240
        .size:           2
        .value_kind:     hidden_group_size_z
      - .offset:         242
        .size:           2
        .value_kind:     hidden_remainder_x
      - .offset:         244
        .size:           2
        .value_kind:     hidden_remainder_y
      - .offset:         246
        .size:           2
        .value_kind:     hidden_remainder_z
      - .offset:         264
        .size:           8
        .value_kind:     hidden_global_offset_x
      - .offset:         272
        .size:           8
        .value_kind:     hidden_global_offset_y
      - .offset:         280
        .size:           8
        .value_kind:     hidden_global_offset_z
      - .offset:         288
        .size:           2
        .value_kind:     hidden_grid_dims
      - .offset:         312
        .size:           8
        .value_kind:     hidden_multigrid_sync_arg
      - .offset:         344
        .size:           4
        .value_kind:     hidden_dynamic_lds_size
    .group_segment_fixed_size: 0
    .kernarg_segment_align: 8
    .kernarg_segment_size: 480
    .language:       OpenCL C
    .language_version:
      - 2
      - 0
    .max_flat_workgroup_size: 512
    .name:           _Z6mk_fwd4Args
    .private_segment_fixed_size: 0
    .sgpr_count:     108
    .sgpr_spill_count: 145
    .symbol:         _Z6mk_fwd4Args.kd
    .uniform_work_group_size: 1
    .uses_dynamic_stack: false
    .vgpr_count:     256
    .vgpr_spill_count: 0
    .wavefront_size: 64
